# scan chunk loops: skip the top-of-loop wait for the previous chunk's Y store acks
# speedup vs baseline: 1.0151x; 1.0043x over previous
; __device__ __forceinline__ unsigned pk2(float lo, float hi) { f32x2n v = {lo, hi}; bf16x2n b = __builtin_convertvector(v, bf16x2n); return __builtin_bit_cast(unsigned, b); }
; DI void ssd_unit(LAS unsigned char* lds, const MixL& P, int b, int g) {
;     ...
; #pragma unroll
;         for (int ti = 0; ti < 4; ++ti) { float s = sq[ti]; s += __shfl_xor(s, 16); s += __shfl_xor(s, 32); if (q == 0) SSQP[wave * 64 + 16 * ti + l15] = s; }
;         asm volatile("s_waitcnt lgkmcnt(0)" ::: "memory"); __builtin_amdgcn_s_barrier(); asm volatile("" ::: "memory");
; #pragma unroll
;         for (int ti = 0; ti < 4; ++ti) { float tot = 0.f;
; #pragma unroll
;             for (int w8 = 0; w8 < 8; ++w8) tot += SSQP[w8 * 64 + 16 * ti + l15];
;             const float rs = __builtin_amdgcn_rsqf(tot * (1.0f / 256.0f) + pg8::RMS_EPS);
; #pragma unroll
;             for (int pt = 0; pt < 2; ++pt) { const f32x4 o = y[pt][ti] * rs * nwv[pt];
;                 u32x2 w2; w2.x = pk2(o[0], o[1]); w2.y = pk2(o[2], o[3]);
;                 *(u32x2*)(P.Y + (rowbase + t0 + 16 * ti + l15) * D + ycol + 16 * pt) = w2; } }
;     }
.LBB0_502:
	s_or_b64 exec, exec, s[24:25]
	s_waitcnt lgkmcnt(0)
	s_barrier
	s_waitcnt lgkmcnt(0)
	ds_read2_b32 v[62:63], v210 offset1:16
	ds_read2_b32 v[64:65], v210 offset0:64 offset1:80
	ds_read2_b32 v[66:67], v210 offset0:128 offset1:144
	ds_read2_b32 v[68:69], v210 offset0:192 offset1:208
	v_add_u32_e32 v92, 0x400, v210
	ds_read2_b32 v[70:71], v92 offset1:16
	s_waitcnt lgkmcnt(4)
	v_add_f32_e32 v9, 0, v62
	ds_read2_b32 v[72:73], v92 offset0:64 offset1:80
	s_waitcnt lgkmcnt(4)
	v_add_f32_e32 v9, v9, v64
	ds_read2_b32 v[86:87], v92 offset0:128 offset1:144
	s_waitcnt lgkmcnt(4)
	v_add_f32_e32 v9, v9, v66
	ds_read2_b32 v[88:89], v92 offset0:192 offset1:208
	s_waitcnt lgkmcnt(4)
	v_add_f32_e32 v9, v9, v68
	s_waitcnt lgkmcnt(3)
	v_add_f32_e32 v9, v9, v70
	s_waitcnt lgkmcnt(2)
	v_add_f32_e32 v9, v9, v72
	s_waitcnt lgkmcnt(1)
	v_add_f32_e32 v9, v9, v86
	s_waitcnt lgkmcnt(0)
	v_add_f32_e32 v9, v9, v88
	v_fmamk_f32 v9, v9, 0x3b800000, v203
	v_rsq_f32_e32 v62, v9
	v_add_f32_e32 v9, 0, v63
	v_add_f32_e32 v9, v9, v65
	v_add_f32_e32 v9, v9, v67
	v_add_f32_e32 v9, v9, v69
	v_pk_mul_f32 v[80:81], v[80:81], v[62:63] op_sel_hi:[1,0]
	v_pk_mul_f32 v[84:85], v[84:85], v[62:63] op_sel_hi:[1,0]
	v_add_f32_e32 v9, v9, v71
	v_pk_mul_f32 v[84:85], v[2:3], v[84:85]
	v_pk_mul_f32 v[80:81], v[0:1], v[80:81]
	v_add_f32_e32 v9, v9, v73
	v_cvt_pk_bf16_f32 v80, v80, v81
	v_cvt_pk_bf16_f32 v81, v84, v85
	v_lshl_add_u64 v[84:85], v[178:179], 0, v[176:177]
	v_add_f32_e32 v9, v9, v87
	v_add_co_u32_e32 v90, vcc, s57, v84
	v_add_f32_e32 v9, v9, v89
	s_nop 0
	v_addc_co_u32_e32 v91, vcc, 0, v85, vcc
	v_fmamk_f32 v9, v9, 0x3b800000, v203
	global_store_dwordx2 v[90:91], v[80:81], off
	v_pk_mul_f32 v[78:79], v[78:79], v[62:63] op_sel_hi:[1,0]
	v_pk_mul_f32 v[80:81], v[82:83], v[62:63] op_sel_hi:[1,0]
	v_rsq_f32_e32 v62, v9
	ds_read2_b32 v[66:67], v92 offset0:32 offset1:48
	ds_read2_b32 v[68:69], v92 offset0:96 offset1:112
	ds_read2_b32 v[70:71], v92 offset0:160 offset1:176
	v_pk_mul_f32 v[60:61], v[60:61], v[62:63] op_sel_hi:[1,0]
	v_pk_mul_f32 v[64:65], v[76:77], v[62:63] op_sel_hi:[1,0]
	v_pk_mul_f32 v[60:61], v[0:1], v[60:61]
	v_pk_mul_f32 v[64:65], v[2:3], v[64:65]
	v_cvt_pk_bf16_f32 v60, v60, v61
	v_cvt_pk_bf16_f32 v61, v64, v65
	v_add_co_u32_e32 v64, vcc, s3, v84
	v_pk_mul_f32 v[58:59], v[58:59], v[62:63] op_sel_hi:[1,0]
	s_nop 0
	v_addc_co_u32_e32 v65, vcc, 0, v85, vcc
	global_store_dwordx2 v[64:65], v[60:61], off
	v_pk_mul_f32 v[60:61], v[74:75], v[62:63] op_sel_hi:[1,0]
	v_pk_mul_f32 v[58:59], v[10:11], v[58:59]
	v_pk_mul_f32 v[60:61], v[12:13], v[60:61]
	v_cvt_pk_bf16_f32 v58, v58, v59
	v_cvt_pk_bf16_f32 v59, v60, v61
	global_store_dwordx2 v[64:65], v[58:59], off offset:32
	ds_read2_b32 v[58:59], v210 offset0:32 offset1:48
	ds_read2_b32 v[60:61], v210 offset0:96 offset1:112
	ds_read2_b32 v[62:63], v210 offset0:160 offset1:176
	ds_read2_b32 v[64:65], v210 offset0:224 offset1:240
	ds_read2_b32 v[72:73], v92 offset0:224 offset1:240
	s_waitcnt lgkmcnt(4)
	v_add_f32_e32 v9, 0, v58
	s_waitcnt lgkmcnt(3)
	v_add_f32_e32 v9, v9, v60
	s_waitcnt lgkmcnt(2)
	v_add_f32_e32 v9, v9, v62
	s_waitcnt lgkmcnt(1)
	v_add_f32_e32 v9, v9, v64
	v_add_f32_e32 v9, v9, v66
	v_add_f32_e32 v9, v9, v68
	v_add_f32_e32 v9, v9, v70
	s_waitcnt lgkmcnt(0)
	v_add_f32_e32 v9, v9, v72
	v_fmamk_f32 v9, v9, 0x3b800000, v203
	v_rsq_f32_e32 v58, v9
	s_add_u32 s70, s70, 0x18000
	v_pk_mul_f32 v[80:81], v[12:13], v[80:81]
	v_pk_mul_f32 v[78:79], v[10:11], v[78:79]
	v_pk_mul_f32 v[46:47], v[46:47], v[58:59] op_sel_hi:[1,0]
	v_pk_mul_f32 v[54:55], v[54:55], v[58:59] op_sel_hi:[1,0]
	v_pk_mul_f32 v[46:47], v[0:1], v[46:47]
	v_pk_mul_f32 v[54:55], v[2:3], v[54:55]
	v_cvt_pk_bf16_f32 v46, v46, v47
	v_cvt_pk_bf16_f32 v47, v54, v55
	v_add_co_u32_e32 v54, vcc, s78, v84
	v_pk_mul_f32 v[4:5], v[4:5], v[58:59] op_sel_hi:[1,0]
	s_nop 0
	v_addc_co_u32_e32 v55, vcc, 0, v85, vcc
	global_store_dwordx2 v[54:55], v[46:47], off
	v_pk_mul_f32 v[46:47], v[50:51], v[58:59] op_sel_hi:[1,0]
	v_pk_mul_f32 v[4:5], v[10:11], v[4:5]
	v_pk_mul_f32 v[46:47], v[12:13], v[46:47]
	v_cvt_pk_bf16_f32 v4, v4, v5
	v_cvt_pk_bf16_f32 v5, v46, v47
	global_store_dwordx2 v[54:55], v[4:5], off offset:32
	v_add_f32_e32 v4, 0, v59
	v_add_f32_e32 v4, v4, v61
	v_add_f32_e32 v4, v4, v63
	v_add_f32_e32 v4, v4, v65
	v_add_f32_e32 v4, v4, v67
	v_add_f32_e32 v4, v4, v69
	v_add_f32_e32 v4, v4, v71
	v_add_f32_e32 v4, v4, v73
	v_fmamk_f32 v4, v4, 0x3b800000, v203
	v_rsq_f32_e32 v4, v4
	s_addc_u32 s71, s71, 0
	s_add_i32 s68, s68, 1
	v_cvt_pk_bf16_f32 v78, v78, v79
	v_pk_mul_f32 v[46:47], v[48:49], v[4:5] op_sel_hi:[1,0]
	v_pk_mul_f32 v[48:49], v[56:57], v[4:5] op_sel_hi:[1,0]
	v_pk_mul_f32 v[46:47], v[0:1], v[46:47]
	v_pk_mul_f32 v[48:49], v[2:3], v[48:49]
	v_pk_mul_f32 v[6:7], v[6:7], v[4:5] op_sel_hi:[1,0]
	v_pk_mul_f32 v[4:5], v[52:53], v[4:5] op_sel_hi:[1,0]
	v_cvt_pk_bf16_f32 v46, v46, v47
	v_cvt_pk_bf16_f32 v47, v48, v49
	v_add_co_u32_e32 v48, vcc, s79, v84
	v_pk_mul_f32 v[4:5], v[12:13], v[4:5]
	v_pk_mul_f32 v[6:7], v[10:11], v[6:7]
	v_cvt_pk_bf16_f32 v79, v80, v81
	v_addc_co_u32_e32 v49, vcc, 0, v85, vcc
	v_cvt_pk_bf16_f32 v6, v6, v7
	v_cvt_pk_bf16_f32 v7, v4, v5
	v_lshl_add_u64 v[178:179], v[178:179], 0, s[76:77]
	v_lshl_add_u64 v[180:181], v[180:181], 0, s[50:51]
	s_cmp_lg_u32 s70, 0x300000
	global_store_dwordx2 v[90:91], v[78:79], off offset:32
	global_store_dwordx2 v[48:49], v[46:47], off
	global_store_dwordx2 v[48:49], v[6:7], off offset:32
	s_cbranch_scc0 .LBB0_521
	v_add_u32_e32 v9, 0, v211
	s_branch .Lssd_top2

; #define LAS __attribute__((address_space(3)))
; DI void ssd_unit(LAS unsigned char* lds, const MixL& P, int b, int g) {
;     ...
;     for (int c = 0; c < SEQ / 64; ++c) {
;         const int t0 = c * 64;
;         asm volatile("s_waitcnt vmcnt(0)" ::: "memory");
; #pragma unroll
;         for (int pass = 0; pass < 2; ++pass) {
;             if (pass == 0 || wave < 4) {
;             const int cgi = pass ? (wave < 2 ? 32 : 40) + (tid & 7) : (tid & 31), run = pass ? ((tid & 127) >> 3) : (tid >> 5);
;             u32x4 rv[4];
; #pragma unroll
;             for (int j = 0; j < 4; ++j) rv[j] = *(const LAS u32x4*)(lds + SSD_STG + (pass ? 32768 + j * 4096 : j * 8192) + tid * 16);
;             u32x2 tv[8];
; #pragma unroll
;             for (int e = 0; e < 8; ++e) { const unsigned a0 = rv[0][e >> 1], a1 = rv[1][e >> 1], a2 = rv[2][e >> 1], a3 = rv[3][e >> 1];
;                 if (e & 1) { tv[e].x = (a0 >> 16) | (a1 & 0xffff0000u); tv[e].y = (a2 >> 16) | (a3 & 0xffff0000u); }
;                 else { tv[e].x = (a0 & 0xffffu) | (a1 << 16); tv[e].y = (a2 & 0xffffu) | (a3 << 16); } }
;             if (cgi < 32) { const int rr = cgi >> 3, p0 = 8 * (cgi & 7);
; #pragma unroll
;                 for (int e = 0; e < 8; ++e) *(LAS u32x2*)(XT + (rr * 64 + p0 + e) * LS + ((run ^ ((cgi & 1) | (((cgi >> 2) & 7) << 1))) << 3)) = tv[e];
;             } else if (cgi < 40) { const int n0 = 8 * (cgi - 32);
; #pragma unroll
;                 for (int j = 0; j < 4; ++j) *(LAS u32x4*)(BMp + (4 * run + j) * LS + n0 * 2) = rv[j];
; #pragma unroll
;                 for (int e = 0; e < 8; ++e) *(LAS u32x2*)(BTp + (n0 + e) * LS + run * 8) = tv[e];
.Lssd_top2:
	v_add_u32_e32 v54, 0x12000, v9
	ds_read_b128 v[4:7], v54
	ds_read_b128 v[46:49], v54 offset:8192
	ds_read_b128 v[50:53], v54 offset:16384
	ds_read_b128 v[54:57], v54 offset:24576
	s_andn2_b64 vcc, exec, s[40:41]
	s_waitcnt lgkmcnt(0)
	v_and_b32_e32 v58, 0xffff, v4
	v_lshrrev_b32_e32 v4, 16, v4
	v_and_or_b32 v60, v46, s26, v4
	v_lshrrev_b32_e32 v4, 16, v50
	v_lshl_or_b32 v58, v46, 16, v58
	v_and_or_b32 v61, v54, s26, v4
	v_and_b32_e32 v4, 0xffff, v5
	v_and_b32_e32 v46, 0xffff, v6
	v_lshrrev_b32_e32 v6, 16, v6
	v_and_b32_e32 v59, 0xffff, v50
	v_lshl_or_b32 v62, v47, 16, v4
	v_and_b32_e32 v4, 0xffff, v51
	v_and_or_b32 v50, v48, s26, v6
	v_lshrrev_b32_e32 v6, 16, v52
	v_lshl_or_b32 v63, v55, 16, v4
	v_lshrrev_b32_e32 v4, 16, v5
	v_lshrrev_b32_e32 v5, 16, v51
	v_and_or_b32 v51, v56, s26, v6
	v_and_b32_e32 v6, 0xffff, v7
	v_lshl_or_b32 v59, v54, 16, v59
	v_and_or_b32 v4, v47, s26, v4
	v_and_b32_e32 v47, 0xffff, v52
	v_lshl_or_b32 v54, v49, 16, v6
	v_and_b32_e32 v6, 0xffff, v53
	v_and_or_b32 v5, v55, s26, v5
	v_lshl_or_b32 v46, v48, 16, v46
	v_lshl_or_b32 v47, v56, 16, v47
	v_lshl_or_b32 v55, v57, 16, v6
	v_lshrrev_b32_e32 v6, 16, v7
	v_lshrrev_b32_e32 v7, 16, v53
	ds_write2_b64 v220, v[58:59], v[60:61] offset1:18
	ds_write2_b64 v220, v[62:63], v[4:5] offset0:36 offset1:54
	ds_write2_b64 v220, v[46:47], v[50:51] offset0:72 offset1:90
	v_cndmask_b32_e64 v4, 0, 1, s[40:41]
	v_and_or_b32 v6, v49, s26, v6
	v_and_or_b32 v7, v57, s26, v7
	v_cmp_ne_u32_e64 s[24:25], 1, v4
	ds_write2_b64 v220, v[54:55], v[6:7] offset0:108 offset1:126
	s_cbranch_vccnz .LBB0_508
	s_add_i32 s33, 0, 0x12000
	v_add_u32_e32 v54, s33, v211
	ds_read_b128 v[4:7], v54 offset:32768
	ds_read_b128 v[46:49], v54 offset:36864
	ds_read_b128 v[50:53], v54 offset:40960
	ds_read_b128 v[54:57], v54 offset:45056
	s_andn2_b64 vcc, exec, s[52:53]
	s_mov_b64 s[54:55], -1
	s_cbranch_vccnz .LBB0_506
	s_mov_b64 s[54:55], 0
	s_waitcnt lgkmcnt(0)
	ds_write_b128 v221, v[4:7] offset:54656
	ds_write_b128 v221, v[46:49] offset:54800
	ds_write_b128 v221, v[50:53] offset:54944
	ds_write_b128 v221, v[54:57] offset:55088

; #define LAS __attribute__((address_space(3)))
; DI void ssd_dma(LAS unsigned char* lds, const MixL& P, size_t rowbase, int b, int g, int c, int tid, int wave) {
;     const int t0 = c * 64;
;     { const int cgi = tid & 31, run = tid >> 5;
;       const int c0 = 256 * g + 8 * cgi;
; #pragma unroll
;       for (int j = 0; j < 4; ++j) __builtin_amdgcn_global_load_lds((const unsigned*)(P.XA + (rowbase + t0 + 4 * run + j) * 768 + c0), (LAS unsigned*)(lds + SSD_STG + j * 8192 + wave * 1024), 16, 0, 0); }
;     if (wave < 4) { const int run = (tid & 127) >> 3;
;       const int c0 = (wave < 2 ? 512 : 640) + 64 * g + 8 * (tid & 7);
; #pragma unroll
;       for (int j = 0; j < 4; ++j) __builtin_amdgcn_global_load_lds((const unsigned*)(P.XA + (rowbase + t0 + 4 * run + j) * 768 + c0), (LAS unsigned*)(lds + SSD_STG + 32768 + j * 4096 + wave * 1024), 16, 0, 0);
;       __builtin_amdgcn_global_load_lds((const unsigned*)(P.DTA + (size_t)(b * 32 + c) * 2048 + wave * 512 + (4 * g + ((tid & 63) >> 4)) * 64 + 4 * (tid & 15)), (LAS unsigned*)(lds + SSD_DT2 + wave * 1024), 16, 0, 0); }
; DI void ssd_unit(LAS unsigned char* lds, const MixL& P, int b, int g) {
;     ...
;         __syncthreads();
;         u32x2 zr[2][4];
; #pragma unroll
;         for (int pt = 0; pt < 2; ++pt)
; #pragma unroll
;             for (int ti = 0; ti < 4; ++ti) zr[pt][ti] = *(const u32x2*)(P.proj + (rowbase + t0 + 16 * ti + l15) * PL + ycol + 16 * pt);
;         if (c + 1 < SEQ / 64) ssd_dma(lds, P, rowbase, b, g, c + 1, tid, wave);
.LBB0_510:
	s_waitcnt lgkmcnt(0)
	v_lshl_add_u64 v[4:5], v[180:181], 0, v[176:177]
	v_add_co_u32_e32 v6, vcc, 0x1b000000, v4
	s_waitcnt vmcnt(8)
	s_nop 0
	v_addc_co_u32_e32 v7, vcc, 0, v5, vcc
	v_add_co_u32_e32 v46, vcc, 0x1b01c000, v4
	s_barrier
	s_nop 0
	v_addc_co_u32_e32 v47, vcc, 0, v5, vcc
	v_add_co_u32_e32 v48, vcc, 0x1b038000, v4
	s_nop 1
	v_addc_co_u32_e32 v49, vcc, 0, v5, vcc
	v_add_co_u32_e32 v4, vcc, 0x1b054000, v4
	s_cmp_eq_u32 s70, 0x2e8000
	s_nop 0
	v_addc_co_u32_e32 v5, vcc, 0, v5, vcc
	global_load_dwordx2 v[196:197], v[6:7], off
	global_load_dwordx2 v[192:193], v[46:47], off
	global_load_dwordx2 v[190:191], v[46:47], off offset:32
	global_load_dwordx2 v[194:195], v[6:7], off offset:32
	global_load_dwordx2 v[188:189], v[48:49], off
	global_load_dwordx2 v[184:185], v[4:5], off
	global_load_dwordx2 v[182:183], v[4:5], off offset:32
	global_load_dwordx2 v[186:187], v[48:49], off offset:32
	s_cbranch_scc1 .LBB0_513
	v_lshl_add_u64 v[4:5], v[174:175], 0, s[70:71]
	s_mov_b64 s[4:5], 0x18000
	s_mov_b32 m0, s1
	v_lshl_add_u64 v[6:7], v[4:5], 0, s[4:5]
	s_mov_b64 s[4:5], 0x18600
	global_load_lds_dwordx4 v[6:7], off
	v_lshl_add_u64 v[6:7], v[4:5], 0, s[4:5]
	s_mov_b32 m0, s56
	s_mov_b64 s[4:5], 0x18c00
	global_load_lds_dwordx4 v[6:7], off
	v_lshl_add_u64 v[6:7], v[4:5], 0, s[4:5]
	s_mov_b32 m0, s81
	v_lshl_add_u64 v[4:5], v[4:5], 0, s[98:99]
	global_load_lds_dwordx4 v[6:7], off
	s_mov_b32 m0, s96
	s_and_b64 vcc, exec, s[24:25]
	global_load_lds_dwordx4 v[4:5], off
	s_cbranch_vccnz .LBB0_513
	v_lshl_add_u64 v[4:5], v[172:173], 0, s[70:71]
	s_mov_b64 s[4:5], 0x18000
	v_lshl_add_u64 v[6:7], v[4:5], 0, s[4:5]
	s_add_i32 m0, s0, 0x1a000
	s_mov_b64 s[4:5], 0x18600
	global_load_lds_dwordx4 v[6:7], off
	v_lshl_add_u64 v[6:7], v[4:5], 0, s[4:5]
	s_add_i32 m0, s0, 0x1b000
	s_mov_b64 s[4:5], 0x18c00
	global_load_lds_dwordx4 v[6:7], off
	v_lshl_add_u64 v[6:7], v[4:5], 0, s[4:5]
	s_add_i32 m0, s0, 0x1c000
	s_ashr_i32 s69, s68, 31
	global_load_lds_dwordx4 v[6:7], off
	v_lshl_add_u64 v[4:5], v[4:5], 0, s[98:99]
	s_add_i32 m0, s0, 0x1d000
	s_lshl_b64 s[24:25], s[68:69], 13
	global_load_lds_dwordx4 v[4:5], off
	v_lshl_add_u64 v[4:5], v[170:171], 0, s[24:25]
	s_add_i32 m0, s0, 0x1e000
	s_nop 0
	global_load_lds_dwordx4 v[4:5], off

; __device__ __forceinline__ unsigned pk2(float lo, float hi) { f32x2n v = {lo, hi}; bf16x2n b = __builtin_convertvector(v, bf16x2n); return __builtin_bit_cast(unsigned, b); }
; #define LAS __attribute__((address_space(3)))
; DI f32x4 mma(bf16x8 a, bf16x8 b, f32x4 c) { return __builtin_amdgcn_mfma_f32_16x16x32_bf16(a, b, c, 0, 0, 0); }
; DI void hg_unit(LAS unsigned char* lds, const MixL& P, int pi) {
;     ...
;         for (int dj = 0; dj < 4; ++dj) { f32x4 a = (f32x4){0.f, 0.f, 0.f, 0.f};
;             a = mma(ld_perm(KET, 16 * dj + l15, 0, q), vtp[0], a); a = mma(ld_perm(KET, 16 * dj + l15, 1, q), vtp[1], a);
;             const f32x4 el = *(const LAS f32x4*)(EBLAST + 16 * dj + 4 * q), elr = *(const LAS f32x4*)(EBLR + 16 * dj + 4 * q);
;             SD[dj] = SD[dj] * el + a * elr; }
; #pragma unroll
;         for (int ti = 0; ti < 4; ++ti) { const f32x4 v = o[ti]; float s = (v[0] * v[0] + v[1] * v[1]) + (v[2] * v[2] + v[3] * v[3]); s += __shfl_xor(s, 16); s += __shfl_xor(s, 32);
;             if (q == 0) SSQP[wv * 64 + 16 * ti + l15] = s; }
;         asm volatile("s_waitcnt lgkmcnt(0)" ::: "memory"); __builtin_amdgcn_s_barrier(); asm volatile("" ::: "memory");
; #pragma unroll
;         for (int ti = 0; ti < 4; ++ti) { const float tot = (SSQP[16 * ti + l15] + SSQP[64 + 16 * ti + l15]) + (SSQP[128 + 16 * ti + l15] + SSQP[192 + 16 * ti + l15]);
;             const float rs = __builtin_amdgcn_rsqf(tot * (1.0f / 64.0f) + pg8::RMS_EPS); const u32x2 gg = gr[ti];
;             const float g0 = __uint_as_float(gg.x << 16), g1 = __uint_as_float(gg.x & 0xffff0000u), g2 = __uint_as_float(gg.y << 16), g3 = __uint_as_float(gg.y & 0xffff0000u);
;             f32x4 ov = o[ti] * rs * nw; ov[0] *= g0; ov[1] *= g1; ov[2] *= g2; ov[3] *= g3;
;             u32x2 w2; w2.x = pk2(ov[0], ov[1]); w2.y = pk2(ov[2], ov[3]);
;             *(u32x2*)(P.Y + (rowbase + t0 + 16 * ti + l15) * D + 512 + ycol) = w2; }
.LBB0_523:
	s_or_b64 exec, exec, s[20:21]
	v_pk_mul_f32 v[32:33], v[32:33], v[36:37]
	v_pk_mul_f32 v[30:31], v[30:31], v[34:35]
	v_pk_fma_f32 v[100:101], v[100:101], v[28:29], v[32:33]
	v_pk_fma_f32 v[98:99], v[98:99], v[26:27], v[30:31]
	v_pk_mul_f32 v[26:27], v[40:41], v[48:49]
	v_pk_mul_f32 v[28:29], v[38:39], v[46:47]
	v_pk_fma_f32 v[104:105], v[104:105], v[44:45], v[26:27]
	v_pk_fma_f32 v[102:103], v[102:103], v[42:43], v[28:29]
	v_pk_mul_f32 v[26:27], v[60:61], v[64:65]
	v_pk_mul_f32 v[28:29], v[58:59], v[62:63]
	s_waitcnt lgkmcnt(0)
	s_barrier
	v_add_u32_e32 v9, 0x9400, v124
	v_add_u32_e32 v38, 0x9800, v124
	v_pk_fma_f32 v[108:109], v[108:109], v[56:57], v[26:27]
	v_pk_fma_f32 v[106:107], v[106:107], v[54:55], v[28:29]
	ds_read2_b32 v[26:27], v9 offset0:192 offset1:208
	ds_read2_b32 v[28:29], v38 offset0:64 offset1:80
	ds_read2_b32 v[30:31], v38 offset1:16
	ds_read2_b32 v[32:33], v38 offset0:128 offset1:144
	v_pk_mul_f32 v[10:11], v[10:11], v[66:67]
	v_pk_mul_f32 v[12:13], v[12:13], v[68:69]
	s_waitcnt lgkmcnt(0)
	v_mov_b32_e32 v35, v28
	v_mov_b32_e32 v34, v26
	v_mov_b32_e32 v36, v30
	v_mov_b32_e32 v37, v32
	v_pk_add_f32 v[34:35], v[34:35], v[36:37]
	v_pk_fma_f32 v[110:111], v[110:111], v[14:15], v[10:11]
	v_add_f32_e32 v26, v34, v35
	v_fmamk_f32 v26, v26, 0x3c800000, v203
	v_rsq_f32_e32 v26, v26
	v_pk_fma_f32 v[112:113], v[112:113], v[16:17], v[12:13]
	s_waitcnt vmcnt(0)
	v_lshlrev_b32_e32 v14, 16, v120
	v_and_b32_e32 v15, 0xffff0000, v120
	v_pk_mul_f32 v[10:11], v[50:51], v[26:27] op_sel_hi:[1,0]
	v_pk_mul_f32 v[12:13], v[52:53], v[26:27] op_sel_hi:[1,0]
	v_pk_mul_f32 v[10:11], v[0:1], v[10:11]
	v_pk_mul_f32 v[12:13], v[2:3], v[12:13]
	v_pk_mul_f32 v[10:11], v[10:11], v[14:15]
	v_lshlrev_b32_e32 v14, 16, v121
	v_and_b32_e32 v15, 0xffff0000, v121
	v_mov_b32_e32 v28, v27
	v_mov_b32_e32 v32, v31
	v_pk_mul_f32 v[12:13], v[12:13], v[14:15]
	v_pk_add_f32 v[14:15], v[28:29], v[32:33]
	v_cvt_pk_bf16_f32 v10, v10, v11
	v_add_f32_e32 v14, v14, v15
	v_fmamk_f32 v14, v14, 0x3c800000, v203
	v_rsq_f32_e32 v14, v14
	v_cvt_pk_bf16_f32 v11, v12, v13
	v_lshl_add_u64 v[12:13], s[30:31], 0, v[94:95]
	v_add_co_u32_e32 v16, vcc, s57, v12
	s_add_i32 s53, s53, -1
	s_nop 0
	v_addc_co_u32_e32 v17, vcc, 0, v13, vcc
	global_store_dwordx2 v[16:17], v[10:11], off offset:1024
	v_pk_mul_f32 v[10:11], v[22:23], v[14:15] op_sel_hi:[1,0]
	v_pk_mul_f32 v[14:15], v[24:25], v[14:15] op_sel_hi:[1,0]
	v_pk_mul_f32 v[10:11], v[0:1], v[10:11]
	v_lshlrev_b32_e32 v16, 16, v118
	v_and_b32_e32 v17, 0xffff0000, v118
	v_pk_mul_f32 v[14:15], v[2:3], v[14:15]
	v_pk_mul_f32 v[10:11], v[10:11], v[16:17]
	v_lshlrev_b32_e32 v16, 16, v119
	v_and_b32_e32 v17, 0xffff0000, v119
	v_pk_mul_f32 v[14:15], v[14:15], v[16:17]
	ds_read2_b32 v[16:17], v9 offset0:224 offset1:240
	ds_read2_b32 v[22:23], v38 offset0:96 offset1:112
	ds_read2_b32 v[24:25], v38 offset0:32 offset1:48
	ds_read2_b32 v[26:27], v38 offset0:160 offset1:176
	v_cvt_pk_bf16_f32 v10, v10, v11
	v_cvt_pk_bf16_f32 v11, v14, v15
	s_waitcnt lgkmcnt(3)
	v_mov_b32_e32 v14, v16
	s_waitcnt lgkmcnt(2)
	v_mov_b32_e32 v15, v22
	s_waitcnt lgkmcnt(1)
	v_mov_b32_e32 v28, v24
	s_waitcnt lgkmcnt(0)
	v_mov_b32_e32 v29, v26
	v_pk_add_f32 v[14:15], v[14:15], v[28:29]
	v_add_co_u32_e32 v28, vcc, s3, v12
	v_add_f32_e32 v9, v14, v15
	v_fmamk_f32 v9, v9, 0x3c800000, v203
	v_rsq_f32_e32 v14, v9
	v_addc_co_u32_e32 v29, vcc, 0, v13, vcc
	global_store_dwordx2 v[28:29], v[10:11], off offset:1024
	v_pk_mul_f32 v[10:11], v[18:19], v[14:15] op_sel_hi:[1,0]
	v_pk_mul_f32 v[14:15], v[20:21], v[14:15] op_sel_hi:[1,0]
	v_pk_mul_f32 v[10:11], v[0:1], v[10:11]
	v_lshlrev_b32_e32 v18, 16, v116
	v_and_b32_e32 v19, 0xffff0000, v116
	v_pk_mul_f32 v[14:15], v[2:3], v[14:15]
	v_pk_mul_f32 v[10:11], v[10:11], v[18:19]
	v_lshlrev_b32_e32 v18, 16, v117
	v_and_b32_e32 v19, 0xffff0000, v117
	v_pk_mul_f32 v[14:15], v[14:15], v[18:19]
	v_mov_b32_e32 v22, v17
	v_mov_b32_e32 v26, v25
	v_cvt_pk_bf16_f32 v10, v10, v11
	v_cvt_pk_bf16_f32 v11, v14, v15
	v_pk_add_f32 v[14:15], v[22:23], v[26:27]
	v_add_co_u32_e32 v16, vcc, s78, v12
	v_add_f32_e32 v9, v14, v15
	v_fmamk_f32 v9, v9, 0x3c800000, v203
	v_rsq_f32_e32 v14, v9
	v_addc_co_u32_e32 v17, vcc, 0, v13, vcc
	global_store_dwordx2 v[16:17], v[10:11], off offset:1024
	v_pk_mul_f32 v[4:5], v[4:5], v[14:15] op_sel_hi:[1,0]
	v_pk_mul_f32 v[6:7], v[6:7], v[14:15] op_sel_hi:[1,0]
	v_pk_mul_f32 v[4:5], v[0:1], v[4:5]
	v_lshlrev_b32_e32 v10, 16, v114
	v_and_b32_e32 v11, 0xffff0000, v114
	v_pk_mul_f32 v[6:7], v[2:3], v[6:7]
	v_pk_mul_f32 v[4:5], v[4:5], v[10:11]
	v_lshlrev_b32_e32 v10, 16, v115
	v_and_b32_e32 v11, 0xffff0000, v115
	v_pk_mul_f32 v[6:7], v[6:7], v[10:11]
	v_cvt_pk_bf16_f32 v4, v4, v5
	v_cvt_pk_bf16_f32 v5, v6, v7
	v_add_co_u32_e32 v6, vcc, s79, v12
	v_lshl_add_u64 v[92:93], v[92:93], 0, s[50:51]
	s_nop 0
	v_addc_co_u32_e32 v7, vcc, 0, v13, vcc
	v_lshl_add_u64 v[94:95], v[94:95], 0, s[76:77]
	s_cmp_lg_u32 s53, 0
	v_lshl_add_u64 v[96:97], v[96:97], 0, s[50:51]
	global_store_dwordx2 v[6:7], v[4:5], off offset:1024
	s_cbranch_scc0 .LBB0_495
	s_branch .Lhg_top2

; #define LAS __attribute__((address_space(3)))
; DI float bf2f(unsigned short h) { return __uint_as_float((unsigned)h << 16); }
; DI void hg_unit(LAS unsigned char* lds, const MixL& P, int pi) {
;     ...
;         asm volatile("s_waitcnt vmcnt(0)" ::: "memory"); __syncthreads();
;         float qv[16], kv[16], cs[16]; unsigned vv[8]; float runs = 0.f;
; #pragma unroll
;         for (int i = 0; i < 16; ++i) { const LAS unsigned char* sp = lds + HG_STG + (i & 1) * 8192 + (chain * 256 + (8 * tq + (i >> 1)) * 8 + (d >> 3)) * 16 + (d & 7) * 2;
;             const float a = bf2f(*(const LAS unsigned short*)(sp + 2 * 8192)), qr = bf2f(*(const LAS unsigned short*)sp); const unsigned vb = *(const LAS unsigned short*)(sp + 4 * 8192);
;             if (i & 1) vv[i >> 1] |= vb << 16; else vv[i >> 1] = vb;
;             const float e = fminf(__expf(-a), 1e30f), sg = __builtin_amdgcn_rcpf(1.0f + e);
;             const float f = lb + oml * sg;
;             runs += __logf(f); cs[i] = runs; qv[i] = qr; kv[i] = oml * (e * sg); }
.Lhg_top2:
	s_waitcnt lgkmcnt(0)
	s_barrier
	ds_read_u16 v210, v130 offset:16384
	ds_read_u16 v211, v144 offset:32768
	ds_read_u16 v212, v130 offset:32768
	ds_read_u16 v213, v131 offset:16384
	ds_read_u16 v214, v131 offset:32768
	ds_read_u16 v215, v132 offset:16384
	ds_read_u16 v216, v132 offset:32768
	ds_read_u16 v217, v133 offset:16384
	ds_read_u16 v218, v133 offset:32768
	ds_read_u16 v219, v134 offset:16384
	ds_read_u16 v220, v134 offset:32768
	ds_read_u16 v221, v135 offset:16384
	ds_read_u16 v222, v135 offset:32768
	ds_read_u16 v223, v136 offset:16384
	ds_read_u16 v224, v136 offset:32768
	ds_read_u16 v225, v137 offset:16384
	ds_read_u16 v226, v137 offset:32768
	ds_read_u16 v227, v138 offset:16384
	ds_read_u16 v228, v138 offset:32768
	ds_read_u16 v229, v139 offset:16384
	ds_read_u16 v230, v139 offset:32768
	ds_read_u16 v231, v140 offset:16384
	ds_read_u16 v232, v140 offset:32768
	ds_read_u16 v233, v141 offset:16384
	ds_read_u16 v234, v141 offset:32768
	ds_read_u16 v235, v142 offset:16384
	ds_read_u16 v236, v142 offset:32768
	ds_read_u16 v237, v143 offset:16384
	ds_read_u16 v238, v143 offset:32768
	ds_read_u16 v239, v144 offset:16384
	ds_read_u16 v240, v145 offset:16384
	ds_read_u16 v241, v145 offset:32768
	s_waitcnt lgkmcnt(0)
	v_mov_b32_e32 v4, v210
	v_mov_b32_e32 v19, v211
	v_mov_b32_e32 v5, v212
	s_waitcnt lgkmcnt(2)
	v_lshlrev_b32_e32 v4, 16, v4
	v_mul_f32_e32 v4, 0xbfb8aa3b, v4
	v_exp_f32_e32 v4, v4
	s_nop 0
	v_min_f32_e32 v14, 0x7149f2ca, v4
	v_add_f32_e32 v4, 1.0, v14
	v_rcp_f32_e32 v16, v4
	s_nop 0
	v_fma_f32 v4, v90, v16, v122
	v_log_f32_e32 v4, v4
	s_nop 0
	v_mul_f32_e32 v6, 0x3f317217, v4
	v_fma_f32 v6, v4, s95, -v6
	v_fmac_f32_e32 v6, 0x3377d1cf, v4
	v_fmac_f32_e32 v6, 0x3f317217, v4
	v_mov_b32_e32 v4, v6
	v_add_f32_e32 v9, 0, v4
	v_mov_b32_e32 v4, v213
	s_waitcnt lgkmcnt(0)
	v_lshlrev_b32_e32 v6, 16, v4
	v_mov_b32_e32 v4, v214
	s_waitcnt lgkmcnt(0)
	v_lshl_or_b32 v4, v4, 16, v5
	v_mul_f32_e32 v5, 0xbfb8aa3b, v6
	v_exp_f32_e32 v5, v5
	s_nop 0
	v_min_f32_e32 v15, 0x7149f2ca, v5
	v_add_f32_e32 v5, 1.0, v15
	v_rcp_f32_e32 v17, v5
	s_nop 0
	v_fma_f32 v5, v90, v17, v122
	v_pk_mul_f32 v[14:15], v[14:15], v[16:17]
	v_log_f32_e32 v5, v5
	v_pk_mul_f32 v[14:15], v[90:91], v[14:15]
	v_mul_f32_e32 v6, 0x3f317217, v5
	v_fma_f32 v6, v5, s95, -v6
	v_fmac_f32_e32 v6, 0x3377d1cf, v5
	v_fmac_f32_e32 v6, 0x3f317217, v5
	v_mov_b32_e32 v5, v6
	v_add_f32_e32 v48, v9, v5
	v_mov_b32_e32 v5, v215
	v_mov_b32_e32 v6, v216
	s_waitcnt lgkmcnt(1)
	v_lshlrev_b32_e32 v5, 16, v5
	v_mul_f32_e32 v5, 0xbfb8aa3b, v5
	v_exp_f32_e32 v5, v5
	s_nop 0
	v_min_f32_e32 v42, 0x7149f2ca, v5
	v_add_f32_e32 v5, 1.0, v42
	v_rcp_f32_e32 v44, v5
	s_nop 0
	v_fma_f32 v5, v90, v44, v122
	v_log_f32_e32 v5, v5
	s_nop 0
	v_mul_f32_e32 v7, 0x3f317217, v5
	v_fma_f32 v7, v5, s95, -v7
	v_fmac_f32_e32 v7, 0x3377d1cf, v5
	v_fmac_f32_e32 v7, 0x3f317217, v5
	v_mov_b32_e32 v5, v7
	v_add_f32_e32 v58, v48, v5
	v_mov_b32_e32 v5, v217
	s_waitcnt lgkmcnt(0)
	v_lshlrev_b32_e32 v7, 16, v5
	v_mov_b32_e32 v5, v218
	s_waitcnt lgkmcnt(0)
	v_lshl_or_b32 v5, v5, 16, v6
	v_mul_f32_e32 v6, 0xbfb8aa3b, v7
	v_exp_f32_e32 v6, v6
	s_nop 0
	v_min_f32_e32 v43, 0x7149f2ca, v6
	v_add_f32_e32 v6, 1.0, v43
	v_rcp_f32_e32 v45, v6
	s_nop 0
	v_fma_f32 v6, v90, v45, v122
	v_pk_mul_f32 v[42:43], v[42:43], v[44:45]
	v_log_f32_e32 v6, v6
	v_pk_mul_f32 v[42:43], v[90:91], v[42:43]
	v_mul_f32_e32 v7, 0x3f317217, v6
	v_fma_f32 v7, v6, s95, -v7
	v_fmac_f32_e32 v7, 0x3377d1cf, v6
	v_fmac_f32_e32 v7, 0x3f317217, v6
	v_mov_b32_e32 v6, v7
	v_add_f32_e32 v62, v58, v6
	v_mov_b32_e32 v6, v219
	v_mov_b32_e32 v7, v220
	s_waitcnt lgkmcnt(1)
	v_lshlrev_b32_e32 v6, 16, v6
	v_mul_f32_e32 v6, 0xbfb8aa3b, v6
	v_exp_f32_e32 v6, v6
	s_nop 0
	v_min_f32_e32 v38, 0x7149f2ca, v6
	v_add_f32_e32 v6, 1.0, v38
	v_rcp_f32_e32 v40, v6
	s_nop 0
	v_fma_f32 v6, v90, v40, v122
	v_log_f32_e32 v6, v6
	s_nop 0
	v_mul_f32_e32 v10, 0x3f317217, v6
	v_fma_f32 v10, v6, s95, -v10
	v_fmac_f32_e32 v10, 0x3377d1cf, v6
	v_fmac_f32_e32 v10, 0x3f317217, v6
	v_mov_b32_e32 v6, v10
	v_add_f32_e32 v56, v62, v6
	v_mov_b32_e32 v6, v221
	s_waitcnt lgkmcnt(0)
	v_lshlrev_b32_e32 v10, 16, v6
	v_mov_b32_e32 v6, v222
	s_waitcnt lgkmcnt(0)
	v_lshl_or_b32 v6, v6, 16, v7
	v_mul_f32_e32 v7, 0xbfb8aa3b, v10
	v_exp_f32_e32 v7, v7
	s_nop 0
	v_min_f32_e32 v39, 0x7149f2ca, v7
	v_add_f32_e32 v7, 1.0, v39
	v_rcp_f32_e32 v41, v7
	s_nop 0
	v_fma_f32 v7, v90, v41, v122
	v_pk_mul_f32 v[38:39], v[38:39], v[40:41]
	v_log_f32_e32 v7, v7
	v_pk_mul_f32 v[38:39], v[90:91], v[38:39]
	v_mul_f32_e32 v10, 0x3f317217, v7
	v_fma_f32 v10, v7, s95, -v10
	v_fmac_f32_e32 v10, 0x3377d1cf, v7
	v_fmac_f32_e32 v10, 0x3f317217, v7
	v_mov_b32_e32 v7, v10
	v_add_f32_e32 v61, v56, v7
	v_mov_b32_e32 v7, v223
	v_mov_b32_e32 v10, v224
	s_waitcnt lgkmcnt(1)
	v_lshlrev_b32_e32 v7, 16, v7
	v_mul_f32_e32 v7, 0xbfb8aa3b, v7
	v_exp_f32_e32 v7, v7
	s_nop 0
	v_min_f32_e32 v34, 0x7149f2ca, v7
	v_add_f32_e32 v7, 1.0, v34
	v_rcp_f32_e32 v36, v7
	s_nop 0
	v_fma_f32 v7, v90, v36, v122
	v_log_f32_e32 v7, v7
	s_nop 0
	v_mul_f32_e32 v11, 0x3f317217, v7
	v_fma_f32 v11, v7, s95, -v11
	v_fmac_f32_e32 v11, 0x3377d1cf, v7
	v_fmac_f32_e32 v11, 0x3f317217, v7
	v_mov_b32_e32 v7, v11
	v_add_f32_e32 v54, v61, v7
	v_mov_b32_e32 v7, v225
	s_waitcnt lgkmcnt(0)
	v_lshlrev_b32_e32 v11, 16, v7
	v_mov_b32_e32 v7, v226
	s_waitcnt lgkmcnt(0)
	v_lshl_or_b32 v7, v7, 16, v10
	v_mul_f32_e32 v10, 0xbfb8aa3b, v11
	v_exp_f32_e32 v10, v10
	s_nop 0
	v_min_f32_e32 v35, 0x7149f2ca, v10
	v_add_f32_e32 v10, 1.0, v35
	v_rcp_f32_e32 v37, v10
	s_nop 0
	v_fma_f32 v10, v90, v37, v122
	v_pk_mul_f32 v[34:35], v[34:35], v[36:37]
	v_log_f32_e32 v10, v10
	v_pk_mul_f32 v[34:35], v[90:91], v[34:35]
	v_mul_f32_e32 v11, 0x3f317217, v10
	v_fma_f32 v11, v10, s95, -v11
	v_fmac_f32_e32 v11, 0x3377d1cf, v10
	v_fmac_f32_e32 v11, 0x3f317217, v10
	v_mov_b32_e32 v10, v11
	v_add_f32_e32 v60, v54, v10
	v_mov_b32_e32 v10, v227
	v_mov_b32_e32 v11, v228
	s_waitcnt lgkmcnt(1)
; #define LAS __attribute__((address_space(3)))
; DI float bf2f(unsigned short h) { return __uint_as_float((unsigned)h << 16); }
; DI void hg_unit(LAS unsigned char* lds, const MixL& P, int pi) {
;     ...
;         float qv[16], kv[16], cs[16]; unsigned vv[8]; float runs = 0.f;
; #pragma unroll
;         for (int i = 0; i < 16; ++i) { const LAS unsigned char* sp = lds + HG_STG + (i & 1) * 8192 + (chain * 256 + (8 * tq + (i >> 1)) * 8 + (d >> 3)) * 16 + (d & 7) * 2;
;             const float a = bf2f(*(const LAS unsigned short*)(sp + 2 * 8192)), qr = bf2f(*(const LAS unsigned short*)sp); const unsigned vb = *(const LAS unsigned short*)(sp + 4 * 8192);
;             if (i & 1) vv[i >> 1] |= vb << 16; else vv[i >> 1] = vb;
;             const float e = fminf(__expf(-a), 1e30f), sg = __builtin_amdgcn_rcpf(1.0f + e);
;             const float f = lb + oml * sg;
;             runs += __logf(f); cs[i] = runs; qv[i] = qr; kv[i] = oml * (e * sg); }
;         CUMQ[tq * 64 + d] = runs;
;         __syncthreads();
	v_lshlrev_b32_e32 v10, 16, v10
	v_mul_f32_e32 v10, 0xbfb8aa3b, v10
	v_exp_f32_e32 v10, v10
	s_nop 0
	v_min_f32_e32 v30, 0x7149f2ca, v10
	v_add_f32_e32 v10, 1.0, v30
	v_rcp_f32_e32 v32, v10
	s_nop 0
	v_fma_f32 v10, v90, v32, v122
	v_log_f32_e32 v10, v10
	s_nop 0
	v_mul_f32_e32 v12, 0x3f317217, v10
	v_fma_f32 v12, v10, s95, -v12
	v_fmac_f32_e32 v12, 0x3377d1cf, v10
	v_fmac_f32_e32 v12, 0x3f317217, v10
	v_mov_b32_e32 v10, v12
	v_add_f32_e32 v52, v60, v10
	v_mov_b32_e32 v10, v229
	s_waitcnt lgkmcnt(0)
	v_lshlrev_b32_e32 v12, 16, v10
	v_mov_b32_e32 v10, v230
	s_waitcnt lgkmcnt(0)
	v_lshl_or_b32 v10, v10, 16, v11
	v_mul_f32_e32 v11, 0xbfb8aa3b, v12
	v_exp_f32_e32 v11, v11
	s_nop 0
	v_min_f32_e32 v31, 0x7149f2ca, v11
	v_add_f32_e32 v11, 1.0, v31
	v_rcp_f32_e32 v33, v11
	s_nop 0
	v_fma_f32 v11, v90, v33, v122
	v_pk_mul_f32 v[30:31], v[30:31], v[32:33]
	v_log_f32_e32 v11, v11
	v_pk_mul_f32 v[30:31], v[90:91], v[30:31]
	v_mul_f32_e32 v12, 0x3f317217, v11
	v_fma_f32 v12, v11, s95, -v12
	v_fmac_f32_e32 v12, 0x3377d1cf, v11
	v_fmac_f32_e32 v12, 0x3f317217, v11
	v_mov_b32_e32 v11, v12
	v_add_f32_e32 v59, v52, v11
	v_mov_b32_e32 v11, v231
	v_mov_b32_e32 v12, v232
	s_waitcnt lgkmcnt(1)
	v_lshlrev_b32_e32 v11, 16, v11
	v_mul_f32_e32 v11, 0xbfb8aa3b, v11
	v_exp_f32_e32 v11, v11
	s_nop 0
	v_min_f32_e32 v26, 0x7149f2ca, v11
	v_add_f32_e32 v11, 1.0, v26
	v_rcp_f32_e32 v28, v11
	s_nop 0
	v_fma_f32 v11, v90, v28, v122
	v_log_f32_e32 v11, v11
	s_nop 0
	v_mul_f32_e32 v13, 0x3f317217, v11
	v_fma_f32 v13, v11, s95, -v13
	v_fmac_f32_e32 v13, 0x3377d1cf, v11
	v_fmac_f32_e32 v13, 0x3f317217, v11
	v_mov_b32_e32 v11, v13
	v_add_f32_e32 v51, v59, v11
	v_mov_b32_e32 v11, v233
	s_waitcnt lgkmcnt(0)
	v_lshlrev_b32_e32 v13, 16, v11
	v_mov_b32_e32 v11, v234
	s_waitcnt lgkmcnt(0)
	v_lshl_or_b32 v11, v11, 16, v12
	v_mul_f32_e32 v12, 0xbfb8aa3b, v13
	v_exp_f32_e32 v12, v12
	s_nop 0
	v_min_f32_e32 v27, 0x7149f2ca, v12
	v_add_f32_e32 v12, 1.0, v27
	v_rcp_f32_e32 v29, v12
	s_nop 0
	v_fma_f32 v12, v90, v29, v122
	v_pk_mul_f32 v[26:27], v[26:27], v[28:29]
	v_log_f32_e32 v12, v12
	v_pk_mul_f32 v[26:27], v[90:91], v[26:27]
	v_mul_f32_e32 v13, 0x3f317217, v12
	v_fma_f32 v13, v12, s95, -v13
	v_fmac_f32_e32 v13, 0x3377d1cf, v12
	v_fmac_f32_e32 v13, 0x3f317217, v12
	v_mov_b32_e32 v12, v13
	v_add_f32_e32 v57, v51, v12
	v_mov_b32_e32 v12, v235
	v_mov_b32_e32 v13, v236
	s_waitcnt lgkmcnt(1)
	v_lshlrev_b32_e32 v12, 16, v12
	v_mul_f32_e32 v12, 0xbfb8aa3b, v12
	v_exp_f32_e32 v12, v12
	s_nop 0
	v_min_f32_e32 v22, 0x7149f2ca, v12
	v_add_f32_e32 v12, 1.0, v22
	v_rcp_f32_e32 v24, v12
	s_nop 0
	v_fma_f32 v12, v90, v24, v122
	v_log_f32_e32 v12, v12
	s_nop 0
	v_mul_f32_e32 v18, 0x3f317217, v12
	v_fma_f32 v18, v12, s95, -v18
	v_fmac_f32_e32 v18, 0x3377d1cf, v12
	v_fmac_f32_e32 v18, 0x3f317217, v12
	v_mov_b32_e32 v12, v18
	v_add_f32_e32 v50, v57, v12
	v_mov_b32_e32 v12, v237
	s_waitcnt lgkmcnt(0)
	v_lshlrev_b32_e32 v18, 16, v12
	v_mov_b32_e32 v12, v238
	s_waitcnt lgkmcnt(0)
	v_lshl_or_b32 v12, v12, 16, v13
	v_mul_f32_e32 v13, 0xbfb8aa3b, v18
	v_exp_f32_e32 v13, v13
	s_nop 0
	v_min_f32_e32 v23, 0x7149f2ca, v13
	v_add_f32_e32 v13, 1.0, v23
	v_rcp_f32_e32 v25, v13
	s_nop 0
	v_fma_f32 v13, v90, v25, v122
	v_pk_mul_f32 v[22:23], v[22:23], v[24:25]
	v_log_f32_e32 v13, v13
	v_pk_mul_f32 v[22:23], v[90:91], v[22:23]
	v_mul_f32_e32 v18, 0x3f317217, v13
	v_fma_f32 v18, v13, s95, -v18
	v_fmac_f32_e32 v18, 0x3377d1cf, v13
	v_fmac_f32_e32 v18, 0x3f317217, v13
	v_mov_b32_e32 v13, v18
	v_add_f32_e32 v55, v50, v13
	v_mov_b32_e32 v13, v239
	s_waitcnt lgkmcnt(0)
	v_lshlrev_b32_e32 v13, 16, v13
	v_mul_f32_e32 v13, 0xbfb8aa3b, v13
	v_exp_f32_e32 v13, v13
	s_nop 0
	v_min_f32_e32 v18, 0x7149f2ca, v13
	v_add_f32_e32 v13, 1.0, v18
	v_rcp_f32_e32 v20, v13
	s_nop 0
	v_fma_f32 v13, v90, v20, v122
	v_log_f32_e32 v13, v13
	s_nop 0
	v_mul_f32_e32 v21, 0x3f317217, v13
	v_fma_f32 v21, v13, s95, -v21
	v_fmac_f32_e32 v21, 0x3377d1cf, v13
	v_fmac_f32_e32 v21, 0x3f317217, v13
	v_mov_b32_e32 v13, v21
	v_add_f32_e32 v49, v55, v13
	v_mov_b32_e32 v13, v240
	s_waitcnt lgkmcnt(0)
	v_lshlrev_b32_e32 v21, 16, v13
	v_mov_b32_e32 v13, v241
	ds_read_u16 v63, v130
	ds_read_u16 v64, v131
	ds_read_u16 v65, v132
	ds_read_u16 v66, v133
	ds_read_u16 v68, v134
	ds_read_u16 v69, v135
	ds_read_u16 v67, v136
	ds_read_u16 v72, v137
	ds_read_u16 v70, v138
	ds_read_u16 v71, v139
	ds_read_u16 v73, v140
	ds_read_u16 v74, v141
	ds_read_u16 v76, v142
	ds_read_u16 v77, v143
	ds_read_u16 v75, v144
	ds_read_u16 v78, v145
	s_waitcnt lgkmcnt(14)
	v_lshlrev_b32_e32 v83, 16, v64
	v_lshlrev_b32_e32 v82, 16, v63
	s_waitcnt lgkmcnt(8)
	v_lshlrev_b32_e32 v41, 16, v72
	v_lshl_or_b32 v13, v13, 16, v19
	v_mul_f32_e32 v19, 0xbfb8aa3b, v21
	v_exp_f32_e32 v19, v19
	v_lshlrev_b32_e32 v40, 16, v67
	s_waitcnt lgkmcnt(6)
	v_lshlrev_b32_e32 v37, 16, v71
	v_lshlrev_b32_e32 v36, 16, v70
	v_min_f32_e32 v19, 0x7149f2ca, v19
	v_add_f32_e32 v21, 1.0, v19
	v_rcp_f32_e32 v21, v21
	s_waitcnt lgkmcnt(2)
	v_lshlrev_b32_e32 v29, 16, v77
	v_lshlrev_b32_e32 v28, 16, v76
	s_waitcnt lgkmcnt(0)
	v_lshlrev_b32_e32 v25, 16, v78
	v_fma_f32 v46, v90, v21, v122
	v_lshlrev_b32_e32 v24, 16, v75
	v_pk_mul_f32 v[18:19], v[18:19], v[20:21]
	v_log_f32_e32 v46, v46
	v_pk_mul_f32 v[18:19], v[90:91], v[18:19]
	v_mul_f32_e32 v47, 0x3f317217, v46
	v_fma_f32 v47, v46, s95, -v47
	v_fmac_f32_e32 v47, 0x3377d1cf, v46
	v_fmac_f32_e32 v47, 0x3f317217, v46
	v_mov_b32_e32 v46, v47
	v_add_f32_e32 v53, v49, v46
	ds_write_b32 v125, v53 offset:37632
	s_waitcnt lgkmcnt(0)
	s_barrier
; __device__ __forceinline__ unsigned pk2(float lo, float hi) { f32x2n v = {lo, hi}; bf16x2n b = __builtin_convertvector(v, bf16x2n); return __builtin_bit_cast(unsigned, b); }
; #define LAS __attribute__((address_space(3)))
; DI void hg_unit(LAS unsigned char* lds, const MixL& P, int pi) {
;     ...
;         { const float c0 = CUMQ[d], c1 = CUMQ[64 + d], c2 = CUMQ[128 + d], c3 = CUMQ[192 + d];
;           const float bref = c0 + c1, blast = bref + (c2 + c3);
;           const float pre = (tq == 0) ? 0.f : (tq == 1 ? c0 : (tq == 2 ? bref : bref + c2));
;           unsigned kt[8];
; #pragma unroll
;           for (int i = 0; i < 16; i += 2) { const float b0 = pre + cs[i], b1 = pre + cs[i + 1];
;               const unsigned qp = pk2(qv[i] * __expf(b0 - bref), qv[i + 1] * __expf(b1 - bref)), kp = pk2(kv[i] * __expf(bref - b0), kv[i + 1] * __expf(bref - b1));
;               *(LAS unsigned short*)(QE + (16 * tq + i) * LS + d * 2) = (unsigned short)(qp & 0xffffu); *(LAS unsigned short*)(QE + (16 * tq + i + 1) * LS + d * 2) = (unsigned short)(qp >> 16);
;               *(LAS unsigned short*)(KE + (16 * tq + i) * LS + d * 2) = (unsigned short)(kp & 0xffffu); *(LAS unsigned short*)(KE + (16 * tq + i + 1) * LS + d * 2) = (unsigned short)(kp >> 16);
;               kt[i >> 1] = kp; }
;           *(LAS u32x4*)(KET + d * LS + tq * 32) = (u32x4){kt[0], kt[1], kt[2], kt[3]}; *(LAS u32x4*)(KET + d * LS + tq * 32 + 16) = (u32x4){kt[4], kt[5], kt[6], kt[7]};
;           *(LAS u32x4*)(VT + d * LS + tq * 32) = (u32x4){vv[0], vv[1], vv[2], vv[3]}; *(LAS u32x4*)(VT + d * LS + tq * 32 + 16) = (u32x4){vv[4], vv[5], vv[6], vv[7]};
;           if (tq == 0) { EBREF[d] = __expf(bref); EBLR[d] = __expf(blast - bref); EBLAST[d] = __expf(blast); } }
	ds_read2st64_b32 v[80:81], v123 offset0:147 offset1:148
	ds_read2st64_b32 v[46:47], v123 offset0:149 offset1:150
	s_andn2_b64 vcc, exec, s[22:23]
	s_waitcnt lgkmcnt(1)
	v_add_f32_e32 v79, v80, v81
	s_waitcnt lgkmcnt(0)
	v_add_f32_e32 v81, v79, v46
	v_cndmask_b32_e64 v81, v81, v79, s[8:9]
	v_cndmask_b32_e64 v80, v81, v80, s[6:7]
	v_cndmask_b32_e64 v84, v80, 0, s[22:23]
	v_add_f32_e32 v9, v9, v84
	v_add_f32_e32 v48, v48, v84
	v_sub_f32_e32 v80, v9, v79
	v_sub_f32_e32 v81, v48, v79
	v_mul_f32_e32 v80, 0x3fb8aa3b, v80
	v_mul_f32_e32 v81, 0x3fb8aa3b, v81
	v_exp_f32_e32 v80, v80
	v_exp_f32_e32 v81, v81
	v_sub_f32_e32 v9, v79, v9
	v_mul_f32_e32 v9, 0x3fb8aa3b, v9
	v_add_f32_e32 v44, v61, v84
	v_pk_mul_f32 v[80:81], v[80:81], v[82:83]
	s_nop 0
	v_cvt_pk_bf16_f32 v63, v80, v81
	v_exp_f32_e32 v80, v9
	v_sub_f32_e32 v9, v79, v48
	v_mul_f32_e32 v9, 0x3fb8aa3b, v9
	v_exp_f32_e32 v81, v9
	v_add_f32_e32 v9, v58, v84
	v_sub_f32_e32 v16, v9, v79
	v_mul_f32_e32 v16, 0x3fb8aa3b, v16
	v_pk_mul_f32 v[14:15], v[14:15], v[80:81]
	v_exp_f32_e32 v16, v16
	v_cvt_pk_bf16_f32 v14, v14, v15
	v_add_f32_e32 v15, v62, v84
	v_sub_f32_e32 v17, v15, v79
	v_mul_f32_e32 v17, 0x3fb8aa3b, v17
	v_exp_f32_e32 v17, v17
	ds_write_b16 v146, v63
	ds_write_b16_d16_hi v146, v63 offset:144
	ds_write_b16 v146, v14 offset:9216
	ds_write_b16_d16_hi v146, v14 offset:9360
	v_lshlrev_b32_e32 v63, 16, v66
	v_lshlrev_b32_e32 v62, 16, v65
	v_sub_f32_e32 v9, v79, v9
	v_pk_mul_f32 v[16:17], v[16:17], v[62:63]
	v_mul_f32_e32 v9, 0x3fb8aa3b, v9
	v_cvt_pk_bf16_f32 v48, v16, v17
	v_exp_f32_e32 v16, v9
	v_sub_f32_e32 v9, v79, v15
	v_mul_f32_e32 v9, 0x3fb8aa3b, v9
	v_exp_f32_e32 v17, v9
	v_add_f32_e32 v9, v56, v84
	v_pk_mul_f32 v[16:17], v[42:43], v[16:17]
	s_nop 0
	v_cvt_pk_bf16_f32 v15, v16, v17
	v_sub_f32_e32 v16, v9, v79
	v_sub_f32_e32 v17, v44, v79
	v_mul_f32_e32 v16, 0x3fb8aa3b, v16
	v_mul_f32_e32 v17, 0x3fb8aa3b, v17
	v_exp_f32_e32 v16, v16
	v_exp_f32_e32 v17, v17
	v_lshlrev_b32_e32 v43, 16, v69
	v_lshlrev_b32_e32 v42, 16, v68
	v_sub_f32_e32 v9, v79, v9
	v_pk_mul_f32 v[16:17], v[16:17], v[42:43]
	v_mul_f32_e32 v9, 0x3fb8aa3b, v9
	v_cvt_pk_bf16_f32 v42, v16, v17
	v_exp_f32_e32 v16, v9
	v_sub_f32_e32 v9, v79, v44
	v_mul_f32_e32 v9, 0x3fb8aa3b, v9
	v_exp_f32_e32 v17, v9
	v_add_f32_e32 v9, v54, v84
	ds_write_b16 v146, v48 offset:288
	ds_write_b16_d16_hi v146, v48 offset:432
	ds_write_b16 v146, v15 offset:9504
	ds_write_b16_d16_hi v146, v15 offset:9648
	v_pk_mul_f32 v[16:17], v[38:39], v[16:17]
	s_nop 0
	v_cvt_pk_bf16_f32 v16, v16, v17
	v_add_f32_e32 v17, v60, v84
	v_sub_f32_e32 v38, v9, v79
	v_sub_f32_e32 v39, v17, v79
	v_mul_f32_e32 v38, 0x3fb8aa3b, v38
	v_mul_f32_e32 v39, 0x3fb8aa3b, v39
	v_exp_f32_e32 v38, v38
	v_exp_f32_e32 v39, v39
	v_sub_f32_e32 v9, v79, v9
	v_mul_f32_e32 v9, 0x3fb8aa3b, v9
	ds_write_b16 v146, v42 offset:576
	ds_write_b16_d16_hi v146, v42 offset:720
	ds_write_b16 v146, v16 offset:9792
	ds_write_b16_d16_hi v146, v16 offset:9936
	v_pk_mul_f32 v[38:39], v[38:39], v[40:41]
	s_nop 0
	v_cvt_pk_bf16_f32 v40, v38, v39
	v_exp_f32_e32 v38, v9
	v_sub_f32_e32 v9, v79, v17
	v_mul_f32_e32 v9, 0x3fb8aa3b, v9
	v_exp_f32_e32 v39, v9
	v_add_f32_e32 v9, v52, v84
	v_pk_mul_f32 v[34:35], v[34:35], v[38:39]
	v_add_f32_e32 v38, v59, v84
	v_cvt_pk_bf16_f32 v17, v34, v35
	v_sub_f32_e32 v34, v9, v79
	v_sub_f32_e32 v35, v38, v79
	v_mul_f32_e32 v34, 0x3fb8aa3b, v34
	v_mul_f32_e32 v35, 0x3fb8aa3b, v35
	v_exp_f32_e32 v34, v34
	v_exp_f32_e32 v35, v35
	v_sub_f32_e32 v9, v79, v9
	v_mul_f32_e32 v9, 0x3fb8aa3b, v9
	ds_write_b16 v146, v40 offset:864
	ds_write_b16_d16_hi v146, v40 offset:1008
	ds_write_b16 v146, v17 offset:10080
	ds_write_b16_d16_hi v146, v17 offset:10224
	v_pk_mul_f32 v[34:35], v[34:35], v[36:37]
	s_nop 0
	v_cvt_pk_bf16_f32 v36, v34, v35
	v_exp_f32_e32 v34, v9
	v_sub_f32_e32 v9, v79, v38
	v_mul_f32_e32 v9, 0x3fb8aa3b, v9
	v_exp_f32_e32 v35, v9
	v_add_f32_e32 v9, v51, v84
	v_sub_f32_e32 v32, v9, v79
	v_mul_f32_e32 v32, 0x3fb8aa3b, v32
	v_pk_mul_f32 v[30:31], v[30:31], v[34:35]
	v_exp_f32_e32 v32, v32
	v_cvt_pk_bf16_f32 v30, v30, v31
	v_add_f32_e32 v31, v57, v84
	v_sub_f32_e32 v33, v31, v79
	v_mul_f32_e32 v33, 0x3fb8aa3b, v33
	v_exp_f32_e32 v33, v33
	v_lshlrev_b32_e32 v35, 16, v74
	v_lshlrev_b32_e32 v34, 16, v73
	v_sub_f32_e32 v9, v79, v9
	v_pk_mul_f32 v[32:33], v[32:33], v[34:35]
	v_mul_f32_e32 v9, 0x3fb8aa3b, v9
	v_cvt_pk_bf16_f32 v34, v32, v33
	v_exp_f32_e32 v32, v9
	v_sub_f32_e32 v9, v79, v31
	v_mul_f32_e32 v9, 0x3fb8aa3b, v9
	v_exp_f32_e32 v33, v9
	v_add_f32_e32 v9, v50, v84
	ds_write_b16 v146, v36 offset:1152
	ds_write_b16_d16_hi v146, v36 offset:1296
	ds_write_b16 v146, v30 offset:10368
	ds_write_b16_d16_hi v146, v30 offset:10512
	v_pk_mul_f32 v[26:27], v[26:27], v[32:33]
	v_add_f32_e32 v32, v55, v84
	v_cvt_pk_bf16_f32 v31, v26, v27
	v_sub_f32_e32 v26, v9, v79
	v_sub_f32_e32 v27, v32, v79
	v_mul_f32_e32 v26, 0x3fb8aa3b, v26
	v_mul_f32_e32 v27, 0x3fb8aa3b, v27
	v_exp_f32_e32 v26, v26
	v_exp_f32_e32 v27, v27
	v_sub_f32_e32 v9, v79, v9
	v_mul_f32_e32 v9, 0x3fb8aa3b, v9
	ds_write_b16 v146, v34 offset:1440
	ds_write_b16_d16_hi v146, v34 offset:1584
	ds_write_b16 v146, v31 offset:10656
	ds_write_b16_d16_hi v146, v31 offset:10800
	v_pk_mul_f32 v[26:27], v[26:27], v[28:29]
	s_nop 0
	v_cvt_pk_bf16_f32 v28, v26, v27
	v_exp_f32_e32 v26, v9
	v_sub_f32_e32 v9, v79, v32
	v_mul_f32_e32 v9, 0x3fb8aa3b, v9
	v_exp_f32_e32 v27, v9
	v_add_f32_e32 v9, v49, v84
	v_pk_mul_f32 v[22:23], v[22:23], v[26:27]
	v_add_f32_e32 v26, v53, v84
	v_cvt_pk_bf16_f32 v32, v22, v23
	v_sub_f32_e32 v22, v9, v79
	v_sub_f32_e32 v23, v26, v79
	v_mul_f32_e32 v22, 0x3fb8aa3b, v22
	v_mul_f32_e32 v23, 0x3fb8aa3b, v23
	v_exp_f32_e32 v22, v22
	v_exp_f32_e32 v23, v23
	v_sub_f32_e32 v9, v79, v9
	v_mul_f32_e32 v9, 0x3fb8aa3b, v9
	ds_write_b16 v146, v28 offset:1728
	ds_write_b16_d16_hi v146, v28 offset:1872
	ds_write_b16 v146, v32 offset:10944
	ds_write_b16_d16_hi v146, v32 offset:11088
	v_pk_mul_f32 v[22:23], v[22:23], v[24:25]
	s_nop 0
	v_cvt_pk_bf16_f32 v24, v22, v23
	v_exp_f32_e32 v22, v9
	v_sub_f32_e32 v9, v79, v26
	v_mul_f32_e32 v9, 0x3fb8aa3b, v9
	v_exp_f32_e32 v23, v9
	v_add_u32_e32 v9, s52, v126
	v_pk_mul_f32 v[18:19], v[18:19], v[22:23]
	s_nop 0
	v_cvt_pk_bf16_f32 v33, v18, v19
	ds_write_b16 v146, v24 offset:2016
	ds_write_b16_d16_hi v146, v24 offset:2160
	ds_write_b16 v146, v33 offset:11232
	ds_write_b16_d16_hi v146, v33 offset:11376
	ds_write_b128 v9, v[14:17] offset:18432
	ds_write_b128 v9, v[30:33] offset:18448
	ds_write_b128 v9, v[4:7] offset:27648
	ds_write_b128 v9, v[10:13] offset:27664
	s_cbranch_vccnz .LBB0_526
	v_add_f32_e32 v4, v46, v47
	v_add_f32_e32 v4, v79, v4
	v_sub_f32_e32 v6, v4, v79
	v_mul_f32_e32 v5, 0x3fb8aa3b, v79
	v_mul_f32_e32 v6, 0x3fb8aa3b, v6
	v_exp_f32_e32 v5, v5
	v_exp_f32_e32 v6, v6
	v_mul_f32_e32 v4, 0x3fb8aa3b, v4
	v_exp_f32_e32 v4, v4
	ds_write2st64_b32 v147, v5, v6 offset0:144 offset1:145
	ds_write_b32 v147, v4 offset:37376
